# speedup vs baseline: 1.0369x; 1.0209x over previous
.LBB0_908:
	v_lshlrev_b64 v[0:1], 28, v[4:5]
	v_ashrrev_i64 v[0:1], 21, v[0:1]
	v_lshlrev_b64 v[14:15], 1, v[0:1]
	v_mov_b32_e32 v128, v129
	v_alignbit_b32 v16, v5, v4, 4
	v_and_b32_e32 v14, 0xfffe0000, v14
	v_mov_b32_e32 v130, v129
	v_mov_b32_e32 v131, v129
	v_mov_b64_e32 v[0:1], v[128:129]
	s_mov_b32 s0, 1
	v_lshl_add_u64 v[12:13], v[6:7], 0, v[14:15]
	v_and_b32_e32 v17, 0x7e0, v16
	s_mov_b64 s[8:9], 0
	v_mov_b64_e32 v[2:3], v[130:131]
	v_cmp_eq_u32_e64 s[0:1], 2, v20
	v_cmp_eq_u32_e64 s[8:9], 4, v20
	v_cmp_eq_u32_e64 s[10:11], 8, v20
	s_mov_b32 s40, 0x1000
	s_mov_b32 s41, 0
	v_lshl_add_u64 v[140:141], v[8:9], 0, v[14:15]
	v_add_co_u32_e32 v142, vcc, 0x29600000, v140
	s_nop 1
	v_addc_co_u32_e32 v143, vcc, 0, v141, vcc
	v_add_co_u32_e32 v140, vcc, 0x25600000, v140
	s_nop 1
	v_addc_co_u32_e32 v141, vcc, 0, v141, vcc
	v_add_co_u32_e32 v26, vcc, 0xffff1000, v140
	s_nop 1
	v_addc_co_u32_e32 v27, vcc, -1, v141, vcc
	v_min_u32_e32 v144, v21, v17
	v_cvt_f32_u32_e32 v145, v20
	v_sub_u32_e32 v145, 0x7f000000, v145
	v_min_u32_e32 v147, 1, v144
	v_sub_u32_e32 v147, 15, v147
	v_lshlrev_b32_e32 v147, 12, v147
	v_add_co_u32_e32 v156, vcc, v26, v147
	s_nop 1
	v_addc_co_u32_e32 v157, vcc, 0, v27, vcc
	global_load_dwordx2 v[68:69], v[156:157], off nt
	v_min_u32_e32 v147, 2, v144
	v_sub_u32_e32 v147, 15, v147
	v_lshlrev_b32_e32 v147, 12, v147
	v_add_co_u32_e32 v156, vcc, v26, v147
	s_nop 1
	v_addc_co_u32_e32 v157, vcc, 0, v27, vcc
	global_load_dwordx2 v[66:67], v[156:157], off nt
	v_min_u32_e32 v147, 3, v144
	v_sub_u32_e32 v147, 15, v147
	v_lshlrev_b32_e32 v147, 12, v147
	v_add_co_u32_e32 v156, vcc, v26, v147
	s_nop 1
	v_addc_co_u32_e32 v157, vcc, 0, v27, vcc
	global_load_dwordx2 v[64:65], v[156:157], off nt
	v_min_u32_e32 v147, 4, v144
	v_sub_u32_e32 v147, 15, v147
	v_lshlrev_b32_e32 v147, 12, v147
	v_add_co_u32_e32 v156, vcc, v26, v147
	s_nop 1
	v_addc_co_u32_e32 v157, vcc, 0, v27, vcc
	global_load_dwordx2 v[62:63], v[156:157], off nt
	v_min_u32_e32 v147, 5, v144
	v_sub_u32_e32 v147, 15, v147
	v_lshlrev_b32_e32 v147, 12, v147
	v_add_co_u32_e32 v156, vcc, v26, v147
	s_nop 1
	v_addc_co_u32_e32 v157, vcc, 0, v27, vcc
	global_load_dwordx2 v[60:61], v[156:157], off nt
	v_min_u32_e32 v147, 6, v144
	v_sub_u32_e32 v147, 15, v147
	v_lshlrev_b32_e32 v147, 12, v147
	v_add_co_u32_e32 v156, vcc, v26, v147
	s_nop 1
	v_addc_co_u32_e32 v157, vcc, 0, v27, vcc
	global_load_dwordx2 v[58:59], v[156:157], off nt
	v_min_u32_e32 v147, 7, v144
	v_sub_u32_e32 v147, 15, v147
	v_lshlrev_b32_e32 v147, 12, v147
	v_add_co_u32_e32 v156, vcc, v26, v147
	s_nop 1
	v_addc_co_u32_e32 v157, vcc, 0, v27, vcc
	global_load_dwordx2 v[56:57], v[156:157], off nt
	v_min_u32_e32 v147, 8, v144
	v_sub_u32_e32 v147, 15, v147
	v_lshlrev_b32_e32 v147, 12, v147
	v_add_co_u32_e32 v156, vcc, v26, v147
	s_nop 1
	v_addc_co_u32_e32 v157, vcc, 0, v27, vcc
	global_load_dwordx2 v[54:55], v[156:157], off nt
	v_min_u32_e32 v147, 9, v144
	v_sub_u32_e32 v147, 15, v147
	v_lshlrev_b32_e32 v147, 12, v147
	v_add_co_u32_e32 v156, vcc, v26, v147
	s_nop 1
	v_addc_co_u32_e32 v157, vcc, 0, v27, vcc
	global_load_dwordx2 v[52:53], v[156:157], off nt
	v_min_u32_e32 v147, 10, v144
	v_sub_u32_e32 v147, 15, v147
	v_lshlrev_b32_e32 v147, 12, v147
	v_add_co_u32_e32 v156, vcc, v26, v147
	s_nop 1
	v_addc_co_u32_e32 v157, vcc, 0, v27, vcc
	global_load_dwordx2 v[50:51], v[156:157], off nt
	v_min_u32_e32 v147, 11, v144
	v_sub_u32_e32 v147, 15, v147
	v_lshlrev_b32_e32 v147, 12, v147
	v_add_co_u32_e32 v156, vcc, v26, v147
	s_nop 1
	v_addc_co_u32_e32 v157, vcc, 0, v27, vcc
	global_load_dwordx2 v[48:49], v[156:157], off nt
	v_min_u32_e32 v147, 12, v144
	v_sub_u32_e32 v147, 15, v147
	v_lshlrev_b32_e32 v147, 12, v147
	v_add_co_u32_e32 v156, vcc, v26, v147
	s_nop 1
	v_addc_co_u32_e32 v157, vcc, 0, v27, vcc
	global_load_dwordx2 v[46:47], v[156:157], off nt
	v_min_u32_e32 v147, 13, v144
	v_sub_u32_e32 v147, 15, v147
	v_lshlrev_b32_e32 v147, 12, v147
	v_add_co_u32_e32 v156, vcc, v26, v147
	s_nop 1
	v_addc_co_u32_e32 v157, vcc, 0, v27, vcc
	global_load_dwordx2 v[44:45], v[156:157], off nt
	v_min_u32_e32 v147, 14, v144
	v_sub_u32_e32 v147, 15, v147
	v_lshlrev_b32_e32 v147, 12, v147
	v_add_co_u32_e32 v156, vcc, v26, v147
	s_nop 1
	v_addc_co_u32_e32 v157, vcc, 0, v27, vcc
	global_load_dwordx2 v[42:43], v[156:157], off nt
	v_min_u32_e32 v147, 15, v144
	v_sub_u32_e32 v147, 15, v147
	v_lshlrev_b32_e32 v147, 12, v147
	v_add_co_u32_e32 v156, vcc, v26, v147
	s_nop 1
	v_addc_co_u32_e32 v157, vcc, 0, v27, vcc
	global_load_dwordx2 v[40:41], v[156:157], off nt
	global_load_dwordx2 v[70:71], v[140:141], off nt
	v_lshl_add_u64 v[140:141], v[140:141], 0, s[40:41]
	global_load_dwordx2 v[72:73], v[140:141], off nt
	v_lshl_add_u64 v[140:141], v[140:141], 0, s[40:41]
	global_load_dwordx2 v[74:75], v[140:141], off nt
	v_lshl_add_u64 v[140:141], v[140:141], 0, s[40:41]
	global_load_dwordx2 v[76:77], v[140:141], off nt
	v_lshl_add_u64 v[140:141], v[140:141], 0, s[40:41]
	global_load_dwordx2 v[78:79], v[140:141], off nt
	v_lshl_add_u64 v[140:141], v[140:141], 0, s[40:41]
	global_load_dwordx2 v[80:81], v[140:141], off nt
	v_lshl_add_u64 v[140:141], v[140:141], 0, s[40:41]
	global_load_dwordx2 v[82:83], v[140:141], off nt
	v_lshl_add_u64 v[140:141], v[140:141], 0, s[40:41]
	global_load_dwordx2 v[84:85], v[140:141], off nt
	v_lshl_add_u64 v[140:141], v[140:141], 0, s[40:41]
	global_load_dwordx2 v[86:87], v[140:141], off nt
	v_lshl_add_u64 v[140:141], v[140:141], 0, s[40:41]
	global_load_dwordx2 v[88:89], v[140:141], off nt
	v_lshl_add_u64 v[140:141], v[140:141], 0, s[40:41]
	global_load_dwordx2 v[90:91], v[140:141], off nt
	v_lshl_add_u64 v[140:141], v[140:141], 0, s[40:41]
	global_load_dwordx2 v[92:93], v[140:141], off nt
	v_lshl_add_u64 v[140:141], v[140:141], 0, s[40:41]
	global_load_dwordx2 v[94:95], v[140:141], off nt
	v_lshl_add_u64 v[140:141], v[140:141], 0, s[40:41]
	global_load_dwordx2 v[96:97], v[140:141], off nt
	v_lshl_add_u64 v[140:141], v[140:141], 0, s[40:41]
	global_load_dwordx2 v[98:99], v[140:141], off nt
	v_lshl_add_u64 v[140:141], v[140:141], 0, s[40:41]
	global_load_dwordx2 v[100:101], v[140:141], off nt
	v_lshl_add_u64 v[140:141], v[140:141], 0, s[40:41]
	global_load_dwordx2 v[102:103], v[140:141], off nt
	v_lshl_add_u64 v[140:141], v[140:141], 0, s[40:41]
	global_load_dwordx2 v[104:105], v[140:141], off nt
	v_lshl_add_u64 v[140:141], v[140:141], 0, s[40:41]
	global_load_dwordx2 v[106:107], v[140:141], off nt
	v_lshl_add_u64 v[140:141], v[140:141], 0, s[40:41]
	global_load_dwordx2 v[108:109], v[140:141], off nt
	v_lshl_add_u64 v[140:141], v[140:141], 0, s[40:41]
	global_load_dwordx2 v[110:111], v[140:141], off nt
	v_lshl_add_u64 v[140:141], v[140:141], 0, s[40:41]
	global_load_dwordx2 v[112:113], v[140:141], off nt
	v_lshl_add_u64 v[140:141], v[140:141], 0, s[40:41]
	global_load_dwordx2 v[114:115], v[140:141], off nt
	v_lshl_add_u64 v[140:141], v[140:141], 0, s[40:41]
	global_load_dwordx2 v[116:117], v[140:141], off nt
	v_lshl_add_u64 v[140:141], v[140:141], 0, s[40:41]
	global_load_dwordx2 v[118:119], v[140:141], off nt
	v_lshl_add_u64 v[140:141], v[140:141], 0, s[40:41]
	global_load_dwordx2 v[120:121], v[140:141], off nt
	v_lshl_add_u64 v[140:141], v[140:141], 0, s[40:41]
	global_load_dwordx2 v[122:123], v[140:141], off nt
	v_lshl_add_u64 v[140:141], v[140:141], 0, s[40:41]
	global_load_dwordx2 v[124:125], v[140:141], off nt
	v_lshl_add_u64 v[140:141], v[140:141], 0, s[40:41]
	global_load_dwordx2 v[132:133], v[140:141], off nt
	v_lshl_add_u64 v[140:141], v[140:141], 0, s[40:41]
	global_load_dwordx2 v[134:135], v[140:141], off nt
	v_lshl_add_u64 v[140:141], v[140:141], 0, s[40:41]
	global_load_dwordx2 v[136:137], v[140:141], off nt
	v_lshl_add_u64 v[140:141], v[140:141], 0, s[40:41]
	global_load_dwordx2 v[138:139], v[140:141], off nt
	s_waitcnt vmcnt(0)
	v_cmp_le_u32_e32 vcc, 1, v144
	s_nop 1
	v_cndmask_b32_e32 v68, 0, v68, vcc
	v_cndmask_b32_e32 v69, 0, v69, vcc
	v_cmp_le_u32_e32 vcc, 2, v144
	s_nop 1
	v_cndmask_b32_e32 v66, 0, v66, vcc
	v_cndmask_b32_e32 v67, 0, v67, vcc
	v_cmp_le_u32_e32 vcc, 3, v144
	s_nop 1
	v_cndmask_b32_e32 v64, 0, v64, vcc
	v_cndmask_b32_e32 v65, 0, v65, vcc
	v_cmp_le_u32_e32 vcc, 4, v144
	s_nop 1
	v_cndmask_b32_e32 v62, 0, v62, vcc
	v_cndmask_b32_e32 v63, 0, v63, vcc
	v_cmp_le_u32_e32 vcc, 5, v144
	s_nop 1
	v_cndmask_b32_e32 v60, 0, v60, vcc
	v_cndmask_b32_e32 v61, 0, v61, vcc
	v_cmp_le_u32_e32 vcc, 6, v144
	s_nop 1
	v_cndmask_b32_e32 v58, 0, v58, vcc
	v_cndmask_b32_e32 v59, 0, v59, vcc
	v_cmp_le_u32_e32 vcc, 7, v144
	s_nop 1
	v_cndmask_b32_e32 v56, 0, v56, vcc
	v_cndmask_b32_e32 v57, 0, v57, vcc
	v_cmp_le_u32_e32 vcc, 8, v144
	s_nop 1
	v_cndmask_b32_e32 v54, 0, v54, vcc
	v_cndmask_b32_e32 v55, 0, v55, vcc
	v_cmp_le_u32_e32 vcc, 9, v144
	s_nop 1
	v_cndmask_b32_e32 v52, 0, v52, vcc
	v_cndmask_b32_e32 v53, 0, v53, vcc
	v_cmp_le_u32_e32 vcc, 10, v144
	s_nop 1
	v_cndmask_b32_e32 v50, 0, v50, vcc
	v_cndmask_b32_e32 v51, 0, v51, vcc
	v_cmp_le_u32_e32 vcc, 11, v144
	s_nop 1
	v_cndmask_b32_e32 v48, 0, v48, vcc
	v_cndmask_b32_e32 v49, 0, v49, vcc
	v_cmp_le_u32_e32 vcc, 12, v144
	s_nop 1
	v_cndmask_b32_e32 v46, 0, v46, vcc
	v_cndmask_b32_e32 v47, 0, v47, vcc
	v_cmp_le_u32_e32 vcc, 13, v144
	s_nop 1
	v_cndmask_b32_e32 v44, 0, v44, vcc
	v_cndmask_b32_e32 v45, 0, v45, vcc
	v_cmp_le_u32_e32 vcc, 14, v144
	s_nop 1
	v_cndmask_b32_e32 v42, 0, v42, vcc
	v_cndmask_b32_e32 v43, 0, v43, vcc
	v_cmp_le_u32_e32 vcc, 15, v144
	s_nop 1
	v_cndmask_b32_e32 v40, 0, v40, vcc
	v_cndmask_b32_e32 v41, 0, v41, vcc
	v_lshlrev_b32_e32 v148, 16, v68
	v_and_b32_e32 v149, 0xffff0000, v68
	v_lshlrev_b32_e32 v150, 16, v69
	v_and_b32_e32 v151, 0xffff0000, v69
	v_add_f32_e32 v2, v2, v150
	v_add_f32_e32 v3, v3, v151
	v_add_f32_e32 v0, v0, v148
	v_add_f32_e32 v1, v1, v149
	v_lshlrev_b32_e32 v148, 16, v66
	v_and_b32_e32 v149, 0xffff0000, v66
	v_lshlrev_b32_e32 v150, 16, v67
	v_and_b32_e32 v151, 0xffff0000, v67
	v_add_f32_e32 v2, v2, v150
	v_add_f32_e32 v3, v3, v151
	v_add_f32_e32 v0, v0, v148
	v_add_f32_e32 v1, v1, v149
	v_lshlrev_b32_e32 v148, 16, v64
	v_and_b32_e32 v149, 0xffff0000, v64
	v_lshlrev_b32_e32 v150, 16, v65
	v_and_b32_e32 v151, 0xffff0000, v65
	v_add_f32_e32 v2, v2, v150
	v_add_f32_e32 v3, v3, v151
	v_add_f32_e32 v0, v0, v148
	v_add_f32_e32 v1, v1, v149
	v_lshlrev_b32_e32 v148, 16, v62
	v_and_b32_e32 v149, 0xffff0000, v62
	v_lshlrev_b32_e32 v150, 16, v63
	v_and_b32_e32 v151, 0xffff0000, v63
	v_add_f32_e32 v2, v2, v150
	v_add_f32_e32 v3, v3, v151
	v_add_f32_e32 v0, v0, v148
	v_add_f32_e32 v1, v1, v149
	v_lshlrev_b32_e32 v148, 16, v60
	v_and_b32_e32 v149, 0xffff0000, v60
	v_lshlrev_b32_e32 v150, 16, v61
	v_and_b32_e32 v151, 0xffff0000, v61
	v_add_f32_e32 v2, v2, v150
	v_add_f32_e32 v3, v3, v151
	v_add_f32_e32 v0, v0, v148
	v_add_f32_e32 v1, v1, v149
	v_lshlrev_b32_e32 v148, 16, v58
	v_and_b32_e32 v149, 0xffff0000, v58
	v_lshlrev_b32_e32 v150, 16, v59
	v_and_b32_e32 v151, 0xffff0000, v59
	v_add_f32_e32 v2, v2, v150
	v_add_f32_e32 v3, v3, v151
	v_add_f32_e32 v0, v0, v148
	v_add_f32_e32 v1, v1, v149
	v_lshlrev_b32_e32 v148, 16, v56
	v_and_b32_e32 v149, 0xffff0000, v56
	v_lshlrev_b32_e32 v150, 16, v57
	v_and_b32_e32 v151, 0xffff0000, v57
	v_add_f32_e32 v2, v2, v150
	v_add_f32_e32 v3, v3, v151
	v_add_f32_e32 v0, v0, v148
	v_add_f32_e32 v1, v1, v149
	v_lshlrev_b32_e32 v148, 16, v54
	v_and_b32_e32 v149, 0xffff0000, v54
	v_lshlrev_b32_e32 v150, 16, v55
	v_and_b32_e32 v151, 0xffff0000, v55
	v_add_f32_e32 v2, v2, v150
	v_add_f32_e32 v3, v3, v151
	v_add_f32_e32 v0, v0, v148
	v_add_f32_e32 v1, v1, v149
	v_lshlrev_b32_e32 v148, 16, v52
	v_and_b32_e32 v149, 0xffff0000, v52
	v_lshlrev_b32_e32 v150, 16, v53
	v_and_b32_e32 v151, 0xffff0000, v53
	v_add_f32_e32 v2, v2, v150
	v_add_f32_e32 v3, v3, v151
	v_add_f32_e32 v0, v0, v148
	v_add_f32_e32 v1, v1, v149
	v_lshlrev_b32_e32 v148, 16, v50
	v_and_b32_e32 v149, 0xffff0000, v50
	v_lshlrev_b32_e32 v150, 16, v51
	v_and_b32_e32 v151, 0xffff0000, v51
	v_add_f32_e32 v2, v2, v150
	v_add_f32_e32 v3, v3, v151
	v_add_f32_e32 v0, v0, v148
	v_add_f32_e32 v1, v1, v149
	v_lshlrev_b32_e32 v148, 16, v48
	v_and_b32_e32 v149, 0xffff0000, v48
	v_lshlrev_b32_e32 v150, 16, v49
	v_and_b32_e32 v151, 0xffff0000, v49
	v_add_f32_e32 v2, v2, v150
	v_add_f32_e32 v3, v3, v151
	v_add_f32_e32 v0, v0, v148
	v_add_f32_e32 v1, v1, v149
	v_lshlrev_b32_e32 v148, 16, v46
	v_and_b32_e32 v149, 0xffff0000, v46
	v_lshlrev_b32_e32 v150, 16, v47
	v_and_b32_e32 v151, 0xffff0000, v47
	v_add_f32_e32 v2, v2, v150
	v_add_f32_e32 v3, v3, v151
	v_add_f32_e32 v0, v0, v148
	v_add_f32_e32 v1, v1, v149
	v_lshlrev_b32_e32 v148, 16, v44
	v_and_b32_e32 v149, 0xffff0000, v44
	v_lshlrev_b32_e32 v150, 16, v45
	v_and_b32_e32 v151, 0xffff0000, v45
	v_add_f32_e32 v2, v2, v150
	v_add_f32_e32 v3, v3, v151
	v_add_f32_e32 v0, v0, v148
	v_add_f32_e32 v1, v1, v149
	v_lshlrev_b32_e32 v148, 16, v42
	v_and_b32_e32 v149, 0xffff0000, v42
	v_lshlrev_b32_e32 v150, 16, v43
	v_and_b32_e32 v151, 0xffff0000, v43
	v_add_f32_e32 v2, v2, v150
	v_add_f32_e32 v3, v3, v151
	v_add_f32_e32 v0, v0, v148
	v_add_f32_e32 v1, v1, v149
	v_lshlrev_b32_e32 v148, 16, v40
	v_and_b32_e32 v149, 0xffff0000, v40
	v_lshlrev_b32_e32 v150, 16, v41
	v_and_b32_e32 v151, 0xffff0000, v41
	v_add_f32_e32 v2, v2, v150
	v_add_f32_e32 v3, v3, v151
	v_add_f32_e32 v0, v0, v148
	v_add_f32_e32 v1, v1, v149
	v_lshlrev_b32_e32 v148, 16, v70
	v_and_b32_e32 v149, 0xffff0000, v70
	v_lshlrev_b32_e32 v150, 16, v71
	v_and_b32_e32 v151, 0xffff0000, v71
	v_add_u32_e32 v147, 1, v17
	v_cmp_ge_u32_e32 vcc, v147, v20
	v_add_f32_e32 v2, v2, v150
	v_add_f32_e32 v3, v3, v151
	v_add_f32_e32 v0, v0, v148
	v_add_f32_e32 v1, v1, v149
	v_mov_b32_e32 v147, 0x3f800000
	v_cndmask_b32_e32 v146, v147, v145, vcc
	v_fma_f32 v152, v146, v0, -v148
	v_fma_f32 v153, v146, v1, -v149
	v_fma_f32 v154, v146, v2, -v150
	v_fma_f32 v155, v146, v3, -v151
	v_cvt_pk_bf16_f32 v152, v152, v153
	v_cvt_pk_bf16_f32 v153, v154, v155
	global_store_dwordx2 v[142:143], v[152:153], off
	v_lshl_add_u64 v[142:143], v[142:143], 0, s[40:41]
	v_cndmask_b32_e64 v156, v40, v56, s[10:11]
	v_cndmask_b32_e64 v156, v156, v64, s[8:9]
	v_cndmask_b32_e64 v156, v156, v68, s[0:1]
	v_cndmask_b32_e64 v157, v41, v57, s[10:11]
	v_cndmask_b32_e64 v157, v157, v65, s[8:9]
	v_cndmask_b32_e64 v157, v157, v69, s[0:1]
	v_lshlrev_b32_e32 v148, 16, v156
	v_and_b32_e32 v149, 0xffff0000, v156
	v_lshlrev_b32_e32 v150, 16, v157
	v_and_b32_e32 v151, 0xffff0000, v157
	v_sub_f32_e32 v3, v3, v151
	v_sub_f32_e32 v2, v2, v150
	v_sub_f32_e32 v1, v1, v149
	v_sub_f32_e32 v0, v0, v148
	v_lshlrev_b32_e32 v148, 16, v72
	v_and_b32_e32 v149, 0xffff0000, v72
	v_lshlrev_b32_e32 v150, 16, v73
	v_and_b32_e32 v151, 0xffff0000, v73
	v_add_u32_e32 v147, 2, v17
	v_cmp_ge_u32_e32 vcc, v147, v20
	v_add_f32_e32 v2, v2, v150
	v_add_f32_e32 v3, v3, v151
	v_add_f32_e32 v0, v0, v148
	v_add_f32_e32 v1, v1, v149
	v_mov_b32_e32 v147, 0x3f000000
	v_cndmask_b32_e32 v146, v147, v145, vcc
	v_fma_f32 v152, v146, v0, -v148
	v_fma_f32 v153, v146, v1, -v149
	v_fma_f32 v154, v146, v2, -v150
	v_fma_f32 v155, v146, v3, -v151
	v_cvt_pk_bf16_f32 v152, v152, v153
	v_cvt_pk_bf16_f32 v153, v154, v155
	global_store_dwordx2 v[142:143], v[152:153], off
	v_lshl_add_u64 v[142:143], v[142:143], 0, s[40:41]
	v_cndmask_b32_e64 v156, v42, v58, s[10:11]
	v_cndmask_b32_e64 v156, v156, v66, s[8:9]
	v_cndmask_b32_e64 v156, v156, v70, s[0:1]
	v_cndmask_b32_e64 v157, v43, v59, s[10:11]
	v_cndmask_b32_e64 v157, v157, v67, s[8:9]
	v_cndmask_b32_e64 v157, v157, v71, s[0:1]
	v_lshlrev_b32_e32 v148, 16, v156
	v_and_b32_e32 v149, 0xffff0000, v156
	v_lshlrev_b32_e32 v150, 16, v157
	v_and_b32_e32 v151, 0xffff0000, v157
	v_sub_f32_e32 v3, v3, v151
	v_sub_f32_e32 v2, v2, v150
	v_sub_f32_e32 v1, v1, v149
	v_sub_f32_e32 v0, v0, v148
	v_lshlrev_b32_e32 v148, 16, v74
	v_and_b32_e32 v149, 0xffff0000, v74
	v_lshlrev_b32_e32 v150, 16, v75
	v_and_b32_e32 v151, 0xffff0000, v75
	v_add_u32_e32 v147, 3, v17
	v_cmp_ge_u32_e32 vcc, v147, v20
	v_add_f32_e32 v2, v2, v150
	v_add_f32_e32 v3, v3, v151
	v_add_f32_e32 v0, v0, v148
	v_add_f32_e32 v1, v1, v149
	v_mov_b32_e32 v147, 0x3eaaaaab
	v_cndmask_b32_e32 v146, v147, v145, vcc
	v_fma_f32 v152, v146, v0, -v148
	v_fma_f32 v153, v146, v1, -v149
	v_fma_f32 v154, v146, v2, -v150
	v_fma_f32 v155, v146, v3, -v151
	v_cvt_pk_bf16_f32 v152, v152, v153
	v_cvt_pk_bf16_f32 v153, v154, v155
	global_store_dwordx2 v[142:143], v[152:153], off
	v_lshl_add_u64 v[142:143], v[142:143], 0, s[40:41]
	v_cndmask_b32_e64 v156, v44, v60, s[10:11]
	v_cndmask_b32_e64 v156, v156, v68, s[8:9]
	v_cndmask_b32_e64 v156, v156, v72, s[0:1]
	v_cndmask_b32_e64 v157, v45, v61, s[10:11]
	v_cndmask_b32_e64 v157, v157, v69, s[8:9]
	v_cndmask_b32_e64 v157, v157, v73, s[0:1]
	v_lshlrev_b32_e32 v148, 16, v156
	v_and_b32_e32 v149, 0xffff0000, v156
	v_lshlrev_b32_e32 v150, 16, v157
	v_and_b32_e32 v151, 0xffff0000, v157
	v_sub_f32_e32 v3, v3, v151
	v_sub_f32_e32 v2, v2, v150
	v_sub_f32_e32 v1, v1, v149
	v_sub_f32_e32 v0, v0, v148
	v_lshlrev_b32_e32 v148, 16, v76
	v_and_b32_e32 v149, 0xffff0000, v76
	v_lshlrev_b32_e32 v150, 16, v77
	v_and_b32_e32 v151, 0xffff0000, v77
	v_add_u32_e32 v147, 4, v17
	v_cmp_ge_u32_e32 vcc, v147, v20
	v_add_f32_e32 v2, v2, v150
	v_add_f32_e32 v3, v3, v151
	v_add_f32_e32 v0, v0, v148
	v_add_f32_e32 v1, v1, v149
	v_mov_b32_e32 v147, 0x3e800000
	v_cndmask_b32_e32 v146, v147, v145, vcc
	v_fma_f32 v152, v146, v0, -v148
	v_fma_f32 v153, v146, v1, -v149
	v_fma_f32 v154, v146, v2, -v150
	v_fma_f32 v155, v146, v3, -v151
	v_cvt_pk_bf16_f32 v152, v152, v153
	v_cvt_pk_bf16_f32 v153, v154, v155
	global_store_dwordx2 v[142:143], v[152:153], off
	v_lshl_add_u64 v[142:143], v[142:143], 0, s[40:41]
	v_cndmask_b32_e64 v156, v46, v62, s[10:11]
	v_cndmask_b32_e64 v156, v156, v70, s[8:9]
	v_cndmask_b32_e64 v156, v156, v74, s[0:1]
	v_cndmask_b32_e64 v157, v47, v63, s[10:11]
	v_cndmask_b32_e64 v157, v157, v71, s[8:9]
	v_cndmask_b32_e64 v157, v157, v75, s[0:1]
	v_lshlrev_b32_e32 v148, 16, v156
	v_and_b32_e32 v149, 0xffff0000, v156
	v_lshlrev_b32_e32 v150, 16, v157
	v_and_b32_e32 v151, 0xffff0000, v157
	v_sub_f32_e32 v3, v3, v151
	v_sub_f32_e32 v2, v2, v150
	v_sub_f32_e32 v1, v1, v149
	v_sub_f32_e32 v0, v0, v148
	v_lshlrev_b32_e32 v148, 16, v78
	v_and_b32_e32 v149, 0xffff0000, v78
	v_lshlrev_b32_e32 v150, 16, v79
	v_and_b32_e32 v151, 0xffff0000, v79
	v_add_u32_e32 v147, 5, v17
	v_cmp_ge_u32_e32 vcc, v147, v20
	v_add_f32_e32 v2, v2, v150
	v_add_f32_e32 v3, v3, v151
	v_add_f32_e32 v0, v0, v148
	v_add_f32_e32 v1, v1, v149
	v_mov_b32_e32 v147, 0x3e4ccccd
	v_cndmask_b32_e32 v146, v147, v145, vcc
	v_fma_f32 v152, v146, v0, -v148
	v_fma_f32 v153, v146, v1, -v149
	v_fma_f32 v154, v146, v2, -v150
	v_fma_f32 v155, v146, v3, -v151
	v_cvt_pk_bf16_f32 v152, v152, v153
	v_cvt_pk_bf16_f32 v153, v154, v155
	global_store_dwordx2 v[142:143], v[152:153], off
	v_lshl_add_u64 v[142:143], v[142:143], 0, s[40:41]
	v_cndmask_b32_e64 v156, v48, v64, s[10:11]
	v_cndmask_b32_e64 v156, v156, v72, s[8:9]
	v_cndmask_b32_e64 v156, v156, v76, s[0:1]
	v_cndmask_b32_e64 v157, v49, v65, s[10:11]
	v_cndmask_b32_e64 v157, v157, v73, s[8:9]
	v_cndmask_b32_e64 v157, v157, v77, s[0:1]
	v_lshlrev_b32_e32 v148, 16, v156
	v_and_b32_e32 v149, 0xffff0000, v156
	v_lshlrev_b32_e32 v150, 16, v157
	v_and_b32_e32 v151, 0xffff0000, v157
	v_sub_f32_e32 v3, v3, v151
	v_sub_f32_e32 v2, v2, v150
	v_sub_f32_e32 v1, v1, v149
	v_sub_f32_e32 v0, v0, v148
	v_lshlrev_b32_e32 v148, 16, v80
	v_and_b32_e32 v149, 0xffff0000, v80
	v_lshlrev_b32_e32 v150, 16, v81
	v_and_b32_e32 v151, 0xffff0000, v81
	v_add_u32_e32 v147, 6, v17
	v_cmp_ge_u32_e32 vcc, v147, v20
	v_add_f32_e32 v2, v2, v150
	v_add_f32_e32 v3, v3, v151
	v_add_f32_e32 v0, v0, v148
	v_add_f32_e32 v1, v1, v149
	v_mov_b32_e32 v147, 0x3e2aaaab
	v_cndmask_b32_e32 v146, v147, v145, vcc
	v_fma_f32 v152, v146, v0, -v148
	v_fma_f32 v153, v146, v1, -v149
	v_fma_f32 v154, v146, v2, -v150
	v_fma_f32 v155, v146, v3, -v151
	v_cvt_pk_bf16_f32 v152, v152, v153
	v_cvt_pk_bf16_f32 v153, v154, v155
	global_store_dwordx2 v[142:143], v[152:153], off
	v_lshl_add_u64 v[142:143], v[142:143], 0, s[40:41]
	v_cndmask_b32_e64 v156, v50, v66, s[10:11]
	v_cndmask_b32_e64 v156, v156, v74, s[8:9]
	v_cndmask_b32_e64 v156, v156, v78, s[0:1]
	v_cndmask_b32_e64 v157, v51, v67, s[10:11]
	v_cndmask_b32_e64 v157, v157, v75, s[8:9]
	v_cndmask_b32_e64 v157, v157, v79, s[0:1]
	v_lshlrev_b32_e32 v148, 16, v156
	v_and_b32_e32 v149, 0xffff0000, v156
	v_lshlrev_b32_e32 v150, 16, v157
	v_and_b32_e32 v151, 0xffff0000, v157
	v_sub_f32_e32 v3, v3, v151
	v_sub_f32_e32 v2, v2, v150
	v_sub_f32_e32 v1, v1, v149
	v_sub_f32_e32 v0, v0, v148
	v_lshlrev_b32_e32 v148, 16, v82
	v_and_b32_e32 v149, 0xffff0000, v82
	v_lshlrev_b32_e32 v150, 16, v83
	v_and_b32_e32 v151, 0xffff0000, v83
	v_add_u32_e32 v147, 7, v17
	v_cmp_ge_u32_e32 vcc, v147, v20
	v_add_f32_e32 v2, v2, v150
	v_add_f32_e32 v3, v3, v151
	v_add_f32_e32 v0, v0, v148
	v_add_f32_e32 v1, v1, v149
	v_mov_b32_e32 v147, 0x3e124925
	v_cndmask_b32_e32 v146, v147, v145, vcc
	v_fma_f32 v152, v146, v0, -v148
	v_fma_f32 v153, v146, v1, -v149
	v_fma_f32 v154, v146, v2, -v150
	v_fma_f32 v155, v146, v3, -v151
	v_cvt_pk_bf16_f32 v152, v152, v153
	v_cvt_pk_bf16_f32 v153, v154, v155
	global_store_dwordx2 v[142:143], v[152:153], off
	v_lshl_add_u64 v[142:143], v[142:143], 0, s[40:41]
	v_cndmask_b32_e64 v156, v52, v68, s[10:11]
	v_cndmask_b32_e64 v156, v156, v76, s[8:9]
	v_cndmask_b32_e64 v156, v156, v80, s[0:1]
	v_cndmask_b32_e64 v157, v53, v69, s[10:11]
	v_cndmask_b32_e64 v157, v157, v77, s[8:9]
	v_cndmask_b32_e64 v157, v157, v81, s[0:1]
	v_lshlrev_b32_e32 v148, 16, v156
	v_and_b32_e32 v149, 0xffff0000, v156
	v_lshlrev_b32_e32 v150, 16, v157
	v_and_b32_e32 v151, 0xffff0000, v157
	v_sub_f32_e32 v3, v3, v151
	v_sub_f32_e32 v2, v2, v150
	v_sub_f32_e32 v1, v1, v149
	v_sub_f32_e32 v0, v0, v148
	v_lshlrev_b32_e32 v148, 16, v84
	v_and_b32_e32 v149, 0xffff0000, v84
	v_lshlrev_b32_e32 v150, 16, v85
	v_and_b32_e32 v151, 0xffff0000, v85
	v_add_u32_e32 v147, 8, v17
	v_cmp_ge_u32_e32 vcc, v147, v20
	v_add_f32_e32 v2, v2, v150
	v_add_f32_e32 v3, v3, v151
	v_add_f32_e32 v0, v0, v148
	v_add_f32_e32 v1, v1, v149
	v_mov_b32_e32 v147, 0x3e000000
	v_cndmask_b32_e32 v146, v147, v145, vcc
	v_fma_f32 v152, v146, v0, -v148
	v_fma_f32 v153, v146, v1, -v149
	v_fma_f32 v154, v146, v2, -v150
	v_fma_f32 v155, v146, v3, -v151
	v_cvt_pk_bf16_f32 v152, v152, v153
	v_cvt_pk_bf16_f32 v153, v154, v155
	global_store_dwordx2 v[142:143], v[152:153], off
	v_lshl_add_u64 v[142:143], v[142:143], 0, s[40:41]
	v_cndmask_b32_e64 v156, v54, v70, s[10:11]
	v_cndmask_b32_e64 v156, v156, v78, s[8:9]
	v_cndmask_b32_e64 v156, v156, v82, s[0:1]
	v_cndmask_b32_e64 v157, v55, v71, s[10:11]
	v_cndmask_b32_e64 v157, v157, v79, s[8:9]
	v_cndmask_b32_e64 v157, v157, v83, s[0:1]
	v_lshlrev_b32_e32 v148, 16, v156
	v_and_b32_e32 v149, 0xffff0000, v156
	v_lshlrev_b32_e32 v150, 16, v157
	v_and_b32_e32 v151, 0xffff0000, v157
	v_sub_f32_e32 v3, v3, v151
	v_sub_f32_e32 v2, v2, v150
	v_sub_f32_e32 v1, v1, v149
	v_sub_f32_e32 v0, v0, v148
	v_lshlrev_b32_e32 v148, 16, v86
	v_and_b32_e32 v149, 0xffff0000, v86
	v_lshlrev_b32_e32 v150, 16, v87
	v_and_b32_e32 v151, 0xffff0000, v87
	v_add_u32_e32 v147, 9, v17
	v_cmp_ge_u32_e32 vcc, v147, v20
	v_add_f32_e32 v2, v2, v150
	v_add_f32_e32 v3, v3, v151
	v_add_f32_e32 v0, v0, v148
	v_add_f32_e32 v1, v1, v149
	v_mov_b32_e32 v147, 0x3de38e39
	v_cndmask_b32_e32 v146, v147, v145, vcc
	v_fma_f32 v152, v146, v0, -v148
	v_fma_f32 v153, v146, v1, -v149
	v_fma_f32 v154, v146, v2, -v150
	v_fma_f32 v155, v146, v3, -v151
	v_cvt_pk_bf16_f32 v152, v152, v153
	v_cvt_pk_bf16_f32 v153, v154, v155
	global_store_dwordx2 v[142:143], v[152:153], off
	v_lshl_add_u64 v[142:143], v[142:143], 0, s[40:41]
	v_cndmask_b32_e64 v156, v56, v72, s[10:11]
	v_cndmask_b32_e64 v156, v156, v80, s[8:9]
	v_cndmask_b32_e64 v156, v156, v84, s[0:1]
	v_cndmask_b32_e64 v157, v57, v73, s[10:11]
	v_cndmask_b32_e64 v157, v157, v81, s[8:9]
	v_cndmask_b32_e64 v157, v157, v85, s[0:1]
	v_lshlrev_b32_e32 v148, 16, v156
	v_and_b32_e32 v149, 0xffff0000, v156
	v_lshlrev_b32_e32 v150, 16, v157
	v_and_b32_e32 v151, 0xffff0000, v157
	v_sub_f32_e32 v3, v3, v151
	v_sub_f32_e32 v2, v2, v150
	v_sub_f32_e32 v1, v1, v149
	v_sub_f32_e32 v0, v0, v148
	v_lshlrev_b32_e32 v148, 16, v88
	v_and_b32_e32 v149, 0xffff0000, v88
	v_lshlrev_b32_e32 v150, 16, v89
	v_and_b32_e32 v151, 0xffff0000, v89
	v_add_u32_e32 v147, 10, v17
	v_cmp_ge_u32_e32 vcc, v147, v20
	v_add_f32_e32 v2, v2, v150
	v_add_f32_e32 v3, v3, v151
	v_add_f32_e32 v0, v0, v148
	v_add_f32_e32 v1, v1, v149
	v_mov_b32_e32 v147, 0x3dcccccd
	v_cndmask_b32_e32 v146, v147, v145, vcc
	v_fma_f32 v152, v146, v0, -v148
	v_fma_f32 v153, v146, v1, -v149
	v_fma_f32 v154, v146, v2, -v150
	v_fma_f32 v155, v146, v3, -v151
	v_cvt_pk_bf16_f32 v152, v152, v153
	v_cvt_pk_bf16_f32 v153, v154, v155
	global_store_dwordx2 v[142:143], v[152:153], off
	v_lshl_add_u64 v[142:143], v[142:143], 0, s[40:41]
	v_cndmask_b32_e64 v156, v58, v74, s[10:11]
	v_cndmask_b32_e64 v156, v156, v82, s[8:9]
	v_cndmask_b32_e64 v156, v156, v86, s[0:1]
	v_cndmask_b32_e64 v157, v59, v75, s[10:11]
	v_cndmask_b32_e64 v157, v157, v83, s[8:9]
	v_cndmask_b32_e64 v157, v157, v87, s[0:1]
	v_lshlrev_b32_e32 v148, 16, v156
	v_and_b32_e32 v149, 0xffff0000, v156
	v_lshlrev_b32_e32 v150, 16, v157
	v_and_b32_e32 v151, 0xffff0000, v157
	v_sub_f32_e32 v3, v3, v151
	v_sub_f32_e32 v2, v2, v150
	v_sub_f32_e32 v1, v1, v149
	v_sub_f32_e32 v0, v0, v148
	v_lshlrev_b32_e32 v148, 16, v90
	v_and_b32_e32 v149, 0xffff0000, v90
	v_lshlrev_b32_e32 v150, 16, v91
	v_and_b32_e32 v151, 0xffff0000, v91
	v_add_u32_e32 v147, 11, v17
	v_cmp_ge_u32_e32 vcc, v147, v20
	v_add_f32_e32 v2, v2, v150
	v_add_f32_e32 v3, v3, v151
	v_add_f32_e32 v0, v0, v148
	v_add_f32_e32 v1, v1, v149
	v_mov_b32_e32 v147, 0x3dba2e8c
	v_cndmask_b32_e32 v146, v147, v145, vcc
	v_fma_f32 v152, v146, v0, -v148
	v_fma_f32 v153, v146, v1, -v149
	v_fma_f32 v154, v146, v2, -v150
	v_fma_f32 v155, v146, v3, -v151
	v_cvt_pk_bf16_f32 v152, v152, v153
	v_cvt_pk_bf16_f32 v153, v154, v155
	global_store_dwordx2 v[142:143], v[152:153], off
	v_lshl_add_u64 v[142:143], v[142:143], 0, s[40:41]
	v_cndmask_b32_e64 v156, v60, v76, s[10:11]
	v_cndmask_b32_e64 v156, v156, v84, s[8:9]
	v_cndmask_b32_e64 v156, v156, v88, s[0:1]
	v_cndmask_b32_e64 v157, v61, v77, s[10:11]
	v_cndmask_b32_e64 v157, v157, v85, s[8:9]
	v_cndmask_b32_e64 v157, v157, v89, s[0:1]
	v_lshlrev_b32_e32 v148, 16, v156
	v_and_b32_e32 v149, 0xffff0000, v156
	v_lshlrev_b32_e32 v150, 16, v157
	v_and_b32_e32 v151, 0xffff0000, v157
	v_sub_f32_e32 v3, v3, v151
	v_sub_f32_e32 v2, v2, v150
	v_sub_f32_e32 v1, v1, v149
	v_sub_f32_e32 v0, v0, v148
	v_lshlrev_b32_e32 v148, 16, v92
	v_and_b32_e32 v149, 0xffff0000, v92
	v_lshlrev_b32_e32 v150, 16, v93
	v_and_b32_e32 v151, 0xffff0000, v93
	v_add_u32_e32 v147, 12, v17
	v_cmp_ge_u32_e32 vcc, v147, v20
	v_add_f32_e32 v2, v2, v150
	v_add_f32_e32 v3, v3, v151
	v_add_f32_e32 v0, v0, v148
	v_add_f32_e32 v1, v1, v149
	v_mov_b32_e32 v147, 0x3daaaaab
	v_cndmask_b32_e32 v146, v147, v145, vcc
	v_fma_f32 v152, v146, v0, -v148
	v_fma_f32 v153, v146, v1, -v149
	v_fma_f32 v154, v146, v2, -v150
	v_fma_f32 v155, v146, v3, -v151
	v_cvt_pk_bf16_f32 v152, v152, v153
	v_cvt_pk_bf16_f32 v153, v154, v155
	global_store_dwordx2 v[142:143], v[152:153], off
	v_lshl_add_u64 v[142:143], v[142:143], 0, s[40:41]
	v_cndmask_b32_e64 v156, v62, v78, s[10:11]
	v_cndmask_b32_e64 v156, v156, v86, s[8:9]
	v_cndmask_b32_e64 v156, v156, v90, s[0:1]
	v_cndmask_b32_e64 v157, v63, v79, s[10:11]
	v_cndmask_b32_e64 v157, v157, v87, s[8:9]
	v_cndmask_b32_e64 v157, v157, v91, s[0:1]
	v_lshlrev_b32_e32 v148, 16, v156
	v_and_b32_e32 v149, 0xffff0000, v156
	v_lshlrev_b32_e32 v150, 16, v157
	v_and_b32_e32 v151, 0xffff0000, v157
	v_sub_f32_e32 v3, v3, v151
	v_sub_f32_e32 v2, v2, v150
	v_sub_f32_e32 v1, v1, v149
	v_sub_f32_e32 v0, v0, v148
	v_lshlrev_b32_e32 v148, 16, v94
	v_and_b32_e32 v149, 0xffff0000, v94
	v_lshlrev_b32_e32 v150, 16, v95
	v_and_b32_e32 v151, 0xffff0000, v95
	v_add_u32_e32 v147, 13, v17
	v_cmp_ge_u32_e32 vcc, v147, v20
	v_add_f32_e32 v2, v2, v150
	v_add_f32_e32 v3, v3, v151
	v_add_f32_e32 v0, v0, v148
	v_add_f32_e32 v1, v1, v149
	v_mov_b32_e32 v147, 0x3d9d89d9
	v_cndmask_b32_e32 v146, v147, v145, vcc
	v_fma_f32 v152, v146, v0, -v148
	v_fma_f32 v153, v146, v1, -v149
	v_fma_f32 v154, v146, v2, -v150
	v_fma_f32 v155, v146, v3, -v151
	v_cvt_pk_bf16_f32 v152, v152, v153
	v_cvt_pk_bf16_f32 v153, v154, v155
	global_store_dwordx2 v[142:143], v[152:153], off
	v_lshl_add_u64 v[142:143], v[142:143], 0, s[40:41]
	v_cndmask_b32_e64 v156, v64, v80, s[10:11]
	v_cndmask_b32_e64 v156, v156, v88, s[8:9]
	v_cndmask_b32_e64 v156, v156, v92, s[0:1]
	v_cndmask_b32_e64 v157, v65, v81, s[10:11]
	v_cndmask_b32_e64 v157, v157, v89, s[8:9]
	v_cndmask_b32_e64 v157, v157, v93, s[0:1]
	v_lshlrev_b32_e32 v148, 16, v156
	v_and_b32_e32 v149, 0xffff0000, v156
	v_lshlrev_b32_e32 v150, 16, v157
	v_and_b32_e32 v151, 0xffff0000, v157
	v_sub_f32_e32 v3, v3, v151
	v_sub_f32_e32 v2, v2, v150
	v_sub_f32_e32 v1, v1, v149
	v_sub_f32_e32 v0, v0, v148
	v_lshlrev_b32_e32 v148, 16, v96
	v_and_b32_e32 v149, 0xffff0000, v96
	v_lshlrev_b32_e32 v150, 16, v97
	v_and_b32_e32 v151, 0xffff0000, v97
	v_add_u32_e32 v147, 14, v17
	v_cmp_ge_u32_e32 vcc, v147, v20
	v_add_f32_e32 v2, v2, v150
	v_add_f32_e32 v3, v3, v151
	v_add_f32_e32 v0, v0, v148
	v_add_f32_e32 v1, v1, v149
	v_mov_b32_e32 v147, 0x3d924925
	v_cndmask_b32_e32 v146, v147, v145, vcc
	v_fma_f32 v152, v146, v0, -v148
	v_fma_f32 v153, v146, v1, -v149
	v_fma_f32 v154, v146, v2, -v150
	v_fma_f32 v155, v146, v3, -v151
	v_cvt_pk_bf16_f32 v152, v152, v153
	v_cvt_pk_bf16_f32 v153, v154, v155
	global_store_dwordx2 v[142:143], v[152:153], off
	v_lshl_add_u64 v[142:143], v[142:143], 0, s[40:41]
	v_cndmask_b32_e64 v156, v66, v82, s[10:11]
	v_cndmask_b32_e64 v156, v156, v90, s[8:9]
	v_cndmask_b32_e64 v156, v156, v94, s[0:1]
	v_cndmask_b32_e64 v157, v67, v83, s[10:11]
	v_cndmask_b32_e64 v157, v157, v91, s[8:9]
	v_cndmask_b32_e64 v157, v157, v95, s[0:1]
	v_lshlrev_b32_e32 v148, 16, v156
	v_and_b32_e32 v149, 0xffff0000, v156
	v_lshlrev_b32_e32 v150, 16, v157
	v_and_b32_e32 v151, 0xffff0000, v157
	v_sub_f32_e32 v3, v3, v151
	v_sub_f32_e32 v2, v2, v150
	v_sub_f32_e32 v1, v1, v149
	v_sub_f32_e32 v0, v0, v148
	v_lshlrev_b32_e32 v148, 16, v98
	v_and_b32_e32 v149, 0xffff0000, v98
	v_lshlrev_b32_e32 v150, 16, v99
	v_and_b32_e32 v151, 0xffff0000, v99
	v_add_u32_e32 v147, 15, v17
	v_cmp_ge_u32_e32 vcc, v147, v20
	v_add_f32_e32 v2, v2, v150
	v_add_f32_e32 v3, v3, v151
	v_add_f32_e32 v0, v0, v148
	v_add_f32_e32 v1, v1, v149
	v_mov_b32_e32 v147, 0x3d888889
	v_cndmask_b32_e32 v146, v147, v145, vcc
	v_fma_f32 v152, v146, v0, -v148
	v_fma_f32 v153, v146, v1, -v149
	v_fma_f32 v154, v146, v2, -v150
	v_fma_f32 v155, v146, v3, -v151
	v_cvt_pk_bf16_f32 v152, v152, v153
	v_cvt_pk_bf16_f32 v153, v154, v155
	global_store_dwordx2 v[142:143], v[152:153], off
	v_lshl_add_u64 v[142:143], v[142:143], 0, s[40:41]
	v_cndmask_b32_e64 v156, v68, v84, s[10:11]
	v_cndmask_b32_e64 v156, v156, v92, s[8:9]
	v_cndmask_b32_e64 v156, v156, v96, s[0:1]
	v_cndmask_b32_e64 v157, v69, v85, s[10:11]
	v_cndmask_b32_e64 v157, v157, v93, s[8:9]
	v_cndmask_b32_e64 v157, v157, v97, s[0:1]
	v_lshlrev_b32_e32 v148, 16, v156
	v_and_b32_e32 v149, 0xffff0000, v156
	v_lshlrev_b32_e32 v150, 16, v157
	v_and_b32_e32 v151, 0xffff0000, v157
	v_sub_f32_e32 v3, v3, v151
	v_sub_f32_e32 v2, v2, v150
	v_sub_f32_e32 v1, v1, v149
	v_sub_f32_e32 v0, v0, v148
	v_lshlrev_b32_e32 v148, 16, v100
	v_and_b32_e32 v149, 0xffff0000, v100
	v_lshlrev_b32_e32 v150, 16, v101
	v_and_b32_e32 v151, 0xffff0000, v101
	v_add_f32_e32 v2, v2, v150
	v_add_f32_e32 v3, v3, v151
	v_add_f32_e32 v0, v0, v148
	v_add_f32_e32 v1, v1, v149
	v_fma_f32 v152, v145, v0, -v148
	v_fma_f32 v153, v145, v1, -v149
	v_fma_f32 v154, v145, v2, -v150
	v_fma_f32 v155, v145, v3, -v151
	v_cvt_pk_bf16_f32 v152, v152, v153
	v_cvt_pk_bf16_f32 v153, v154, v155
	global_store_dwordx2 v[142:143], v[152:153], off
	v_lshl_add_u64 v[142:143], v[142:143], 0, s[40:41]
	v_cndmask_b32_e64 v156, v70, v86, s[10:11]
	v_cndmask_b32_e64 v156, v156, v94, s[8:9]
	v_cndmask_b32_e64 v156, v156, v98, s[0:1]
	v_cndmask_b32_e64 v157, v71, v87, s[10:11]
	v_cndmask_b32_e64 v157, v157, v95, s[8:9]
	v_cndmask_b32_e64 v157, v157, v99, s[0:1]
	v_lshlrev_b32_e32 v148, 16, v156
	v_and_b32_e32 v149, 0xffff0000, v156
	v_lshlrev_b32_e32 v150, 16, v157
	v_and_b32_e32 v151, 0xffff0000, v157
	v_sub_f32_e32 v3, v3, v151
	v_sub_f32_e32 v2, v2, v150
	v_sub_f32_e32 v1, v1, v149
	v_sub_f32_e32 v0, v0, v148
	v_lshlrev_b32_e32 v148, 16, v102
	v_and_b32_e32 v149, 0xffff0000, v102
	v_lshlrev_b32_e32 v150, 16, v103
	v_and_b32_e32 v151, 0xffff0000, v103
	v_add_f32_e32 v2, v2, v150
	v_add_f32_e32 v3, v3, v151
	v_add_f32_e32 v0, v0, v148
	v_add_f32_e32 v1, v1, v149
	v_fma_f32 v152, v145, v0, -v148
	v_fma_f32 v153, v145, v1, -v149
	v_fma_f32 v154, v145, v2, -v150
	v_fma_f32 v155, v145, v3, -v151
	v_cvt_pk_bf16_f32 v152, v152, v153
	v_cvt_pk_bf16_f32 v153, v154, v155
	global_store_dwordx2 v[142:143], v[152:153], off
	v_lshl_add_u64 v[142:143], v[142:143], 0, s[40:41]
	v_cndmask_b32_e64 v156, v72, v88, s[10:11]
	v_cndmask_b32_e64 v156, v156, v96, s[8:9]
	v_cndmask_b32_e64 v156, v156, v100, s[0:1]
	v_cndmask_b32_e64 v157, v73, v89, s[10:11]
	v_cndmask_b32_e64 v157, v157, v97, s[8:9]
	v_cndmask_b32_e64 v157, v157, v101, s[0:1]
	v_lshlrev_b32_e32 v148, 16, v156
	v_and_b32_e32 v149, 0xffff0000, v156
	v_lshlrev_b32_e32 v150, 16, v157
	v_and_b32_e32 v151, 0xffff0000, v157
	v_sub_f32_e32 v3, v3, v151
	v_sub_f32_e32 v2, v2, v150
	v_sub_f32_e32 v1, v1, v149
	v_sub_f32_e32 v0, v0, v148
	v_lshlrev_b32_e32 v148, 16, v104
	v_and_b32_e32 v149, 0xffff0000, v104
	v_lshlrev_b32_e32 v150, 16, v105
	v_and_b32_e32 v151, 0xffff0000, v105
	v_add_f32_e32 v2, v2, v150
	v_add_f32_e32 v3, v3, v151
	v_add_f32_e32 v0, v0, v148
	v_add_f32_e32 v1, v1, v149
	v_fma_f32 v152, v145, v0, -v148
	v_fma_f32 v153, v145, v1, -v149
	v_fma_f32 v154, v145, v2, -v150
	v_fma_f32 v155, v145, v3, -v151
	v_cvt_pk_bf16_f32 v152, v152, v153
	v_cvt_pk_bf16_f32 v153, v154, v155
	global_store_dwordx2 v[142:143], v[152:153], off
	v_lshl_add_u64 v[142:143], v[142:143], 0, s[40:41]
	v_cndmask_b32_e64 v156, v74, v90, s[10:11]
	v_cndmask_b32_e64 v156, v156, v98, s[8:9]
	v_cndmask_b32_e64 v156, v156, v102, s[0:1]
	v_cndmask_b32_e64 v157, v75, v91, s[10:11]
	v_cndmask_b32_e64 v157, v157, v99, s[8:9]
	v_cndmask_b32_e64 v157, v157, v103, s[0:1]
	v_lshlrev_b32_e32 v148, 16, v156
	v_and_b32_e32 v149, 0xffff0000, v156
	v_lshlrev_b32_e32 v150, 16, v157
	v_and_b32_e32 v151, 0xffff0000, v157
	v_sub_f32_e32 v3, v3, v151
	v_sub_f32_e32 v2, v2, v150
	v_sub_f32_e32 v1, v1, v149
	v_sub_f32_e32 v0, v0, v148
	v_lshlrev_b32_e32 v148, 16, v106
	v_and_b32_e32 v149, 0xffff0000, v106
	v_lshlrev_b32_e32 v150, 16, v107
	v_and_b32_e32 v151, 0xffff0000, v107
	v_add_f32_e32 v2, v2, v150
	v_add_f32_e32 v3, v3, v151
	v_add_f32_e32 v0, v0, v148
	v_add_f32_e32 v1, v1, v149
	v_fma_f32 v152, v145, v0, -v148
	v_fma_f32 v153, v145, v1, -v149
	v_fma_f32 v154, v145, v2, -v150
	v_fma_f32 v155, v145, v3, -v151
	v_cvt_pk_bf16_f32 v152, v152, v153
	v_cvt_pk_bf16_f32 v153, v154, v155
	global_store_dwordx2 v[142:143], v[152:153], off
	v_lshl_add_u64 v[142:143], v[142:143], 0, s[40:41]
	v_cndmask_b32_e64 v156, v76, v92, s[10:11]
	v_cndmask_b32_e64 v156, v156, v100, s[8:9]
	v_cndmask_b32_e64 v156, v156, v104, s[0:1]
	v_cndmask_b32_e64 v157, v77, v93, s[10:11]
	v_cndmask_b32_e64 v157, v157, v101, s[8:9]
	v_cndmask_b32_e64 v157, v157, v105, s[0:1]
	v_lshlrev_b32_e32 v148, 16, v156
	v_and_b32_e32 v149, 0xffff0000, v156
	v_lshlrev_b32_e32 v150, 16, v157
	v_and_b32_e32 v151, 0xffff0000, v157
	v_sub_f32_e32 v3, v3, v151
	v_sub_f32_e32 v2, v2, v150
	v_sub_f32_e32 v1, v1, v149
	v_sub_f32_e32 v0, v0, v148
	v_lshlrev_b32_e32 v148, 16, v108
	v_and_b32_e32 v149, 0xffff0000, v108
	v_lshlrev_b32_e32 v150, 16, v109
	v_and_b32_e32 v151, 0xffff0000, v109
	v_add_f32_e32 v2, v2, v150
	v_add_f32_e32 v3, v3, v151
	v_add_f32_e32 v0, v0, v148
	v_add_f32_e32 v1, v1, v149
	v_fma_f32 v152, v145, v0, -v148
	v_fma_f32 v153, v145, v1, -v149
	v_fma_f32 v154, v145, v2, -v150
	v_fma_f32 v155, v145, v3, -v151
	v_cvt_pk_bf16_f32 v152, v152, v153
	v_cvt_pk_bf16_f32 v153, v154, v155
	global_store_dwordx2 v[142:143], v[152:153], off
	v_lshl_add_u64 v[142:143], v[142:143], 0, s[40:41]
	v_cndmask_b32_e64 v156, v78, v94, s[10:11]
	v_cndmask_b32_e64 v156, v156, v102, s[8:9]
	v_cndmask_b32_e64 v156, v156, v106, s[0:1]
	v_cndmask_b32_e64 v157, v79, v95, s[10:11]
	v_cndmask_b32_e64 v157, v157, v103, s[8:9]
	v_cndmask_b32_e64 v157, v157, v107, s[0:1]
	v_lshlrev_b32_e32 v148, 16, v156
	v_and_b32_e32 v149, 0xffff0000, v156
	v_lshlrev_b32_e32 v150, 16, v157
	v_and_b32_e32 v151, 0xffff0000, v157
	v_sub_f32_e32 v3, v3, v151
	v_sub_f32_e32 v2, v2, v150
	v_sub_f32_e32 v1, v1, v149
	v_sub_f32_e32 v0, v0, v148
	v_lshlrev_b32_e32 v148, 16, v110
	v_and_b32_e32 v149, 0xffff0000, v110
	v_lshlrev_b32_e32 v150, 16, v111
	v_and_b32_e32 v151, 0xffff0000, v111
	v_add_f32_e32 v2, v2, v150
	v_add_f32_e32 v3, v3, v151
	v_add_f32_e32 v0, v0, v148
	v_add_f32_e32 v1, v1, v149
	v_fma_f32 v152, v145, v0, -v148
	v_fma_f32 v153, v145, v1, -v149
	v_fma_f32 v154, v145, v2, -v150
	v_fma_f32 v155, v145, v3, -v151
	v_cvt_pk_bf16_f32 v152, v152, v153
	v_cvt_pk_bf16_f32 v153, v154, v155
	global_store_dwordx2 v[142:143], v[152:153], off
	v_lshl_add_u64 v[142:143], v[142:143], 0, s[40:41]
	v_cndmask_b32_e64 v156, v80, v96, s[10:11]
	v_cndmask_b32_e64 v156, v156, v104, s[8:9]
	v_cndmask_b32_e64 v156, v156, v108, s[0:1]
	v_cndmask_b32_e64 v157, v81, v97, s[10:11]
	v_cndmask_b32_e64 v157, v157, v105, s[8:9]
	v_cndmask_b32_e64 v157, v157, v109, s[0:1]
	v_lshlrev_b32_e32 v148, 16, v156
	v_and_b32_e32 v149, 0xffff0000, v156
	v_lshlrev_b32_e32 v150, 16, v157
	v_and_b32_e32 v151, 0xffff0000, v157
	v_sub_f32_e32 v3, v3, v151
	v_sub_f32_e32 v2, v2, v150
	v_sub_f32_e32 v1, v1, v149
	v_sub_f32_e32 v0, v0, v148
	v_lshlrev_b32_e32 v148, 16, v112
	v_and_b32_e32 v149, 0xffff0000, v112
	v_lshlrev_b32_e32 v150, 16, v113
	v_and_b32_e32 v151, 0xffff0000, v113
	v_add_f32_e32 v2, v2, v150
	v_add_f32_e32 v3, v3, v151
	v_add_f32_e32 v0, v0, v148
	v_add_f32_e32 v1, v1, v149
	v_fma_f32 v152, v145, v0, -v148
	v_fma_f32 v153, v145, v1, -v149
	v_fma_f32 v154, v145, v2, -v150
	v_fma_f32 v155, v145, v3, -v151
	v_cvt_pk_bf16_f32 v152, v152, v153
	v_cvt_pk_bf16_f32 v153, v154, v155
	global_store_dwordx2 v[142:143], v[152:153], off
	v_lshl_add_u64 v[142:143], v[142:143], 0, s[40:41]
	v_cndmask_b32_e64 v156, v82, v98, s[10:11]
	v_cndmask_b32_e64 v156, v156, v106, s[8:9]
	v_cndmask_b32_e64 v156, v156, v110, s[0:1]
	v_cndmask_b32_e64 v157, v83, v99, s[10:11]
	v_cndmask_b32_e64 v157, v157, v107, s[8:9]
	v_cndmask_b32_e64 v157, v157, v111, s[0:1]
	v_lshlrev_b32_e32 v148, 16, v156
	v_and_b32_e32 v149, 0xffff0000, v156
	v_lshlrev_b32_e32 v150, 16, v157
	v_and_b32_e32 v151, 0xffff0000, v157
	v_sub_f32_e32 v3, v3, v151
	v_sub_f32_e32 v2, v2, v150
	v_sub_f32_e32 v1, v1, v149
	v_sub_f32_e32 v0, v0, v148
	v_lshlrev_b32_e32 v148, 16, v114
	v_and_b32_e32 v149, 0xffff0000, v114
	v_lshlrev_b32_e32 v150, 16, v115
	v_and_b32_e32 v151, 0xffff0000, v115
	v_add_f32_e32 v2, v2, v150
	v_add_f32_e32 v3, v3, v151
	v_add_f32_e32 v0, v0, v148
	v_add_f32_e32 v1, v1, v149
	v_fma_f32 v152, v145, v0, -v148
	v_fma_f32 v153, v145, v1, -v149
	v_fma_f32 v154, v145, v2, -v150
	v_fma_f32 v155, v145, v3, -v151
	v_cvt_pk_bf16_f32 v152, v152, v153
	v_cvt_pk_bf16_f32 v153, v154, v155
	global_store_dwordx2 v[142:143], v[152:153], off
	v_lshl_add_u64 v[142:143], v[142:143], 0, s[40:41]
	v_cndmask_b32_e64 v156, v84, v100, s[10:11]
	v_cndmask_b32_e64 v156, v156, v108, s[8:9]
	v_cndmask_b32_e64 v156, v156, v112, s[0:1]
	v_cndmask_b32_e64 v157, v85, v101, s[10:11]
	v_cndmask_b32_e64 v157, v157, v109, s[8:9]
	v_cndmask_b32_e64 v157, v157, v113, s[0:1]
	v_lshlrev_b32_e32 v148, 16, v156
	v_and_b32_e32 v149, 0xffff0000, v156
	v_lshlrev_b32_e32 v150, 16, v157
	v_and_b32_e32 v151, 0xffff0000, v157
	v_sub_f32_e32 v3, v3, v151
	v_sub_f32_e32 v2, v2, v150
	v_sub_f32_e32 v1, v1, v149
	v_sub_f32_e32 v0, v0, v148
	v_lshlrev_b32_e32 v148, 16, v116
	v_and_b32_e32 v149, 0xffff0000, v116
	v_lshlrev_b32_e32 v150, 16, v117
	v_and_b32_e32 v151, 0xffff0000, v117
	v_add_f32_e32 v2, v2, v150
	v_add_f32_e32 v3, v3, v151
	v_add_f32_e32 v0, v0, v148
	v_add_f32_e32 v1, v1, v149
	v_fma_f32 v152, v145, v0, -v148
	v_fma_f32 v153, v145, v1, -v149
	v_fma_f32 v154, v145, v2, -v150
	v_fma_f32 v155, v145, v3, -v151
	v_cvt_pk_bf16_f32 v152, v152, v153
	v_cvt_pk_bf16_f32 v153, v154, v155
	global_store_dwordx2 v[142:143], v[152:153], off
	v_lshl_add_u64 v[142:143], v[142:143], 0, s[40:41]
	v_cndmask_b32_e64 v156, v86, v102, s[10:11]
	v_cndmask_b32_e64 v156, v156, v110, s[8:9]
	v_cndmask_b32_e64 v156, v156, v114, s[0:1]
	v_cndmask_b32_e64 v157, v87, v103, s[10:11]
	v_cndmask_b32_e64 v157, v157, v111, s[8:9]
	v_cndmask_b32_e64 v157, v157, v115, s[0:1]
	v_lshlrev_b32_e32 v148, 16, v156
	v_and_b32_e32 v149, 0xffff0000, v156
	v_lshlrev_b32_e32 v150, 16, v157
	v_and_b32_e32 v151, 0xffff0000, v157
	v_sub_f32_e32 v3, v3, v151
	v_sub_f32_e32 v2, v2, v150
	v_sub_f32_e32 v1, v1, v149
	v_sub_f32_e32 v0, v0, v148
	v_lshlrev_b32_e32 v148, 16, v118
	v_and_b32_e32 v149, 0xffff0000, v118
	v_lshlrev_b32_e32 v150, 16, v119
	v_and_b32_e32 v151, 0xffff0000, v119
	v_add_f32_e32 v2, v2, v150
	v_add_f32_e32 v3, v3, v151
	v_add_f32_e32 v0, v0, v148
	v_add_f32_e32 v1, v1, v149
	v_fma_f32 v152, v145, v0, -v148
	v_fma_f32 v153, v145, v1, -v149
	v_fma_f32 v154, v145, v2, -v150
	v_fma_f32 v155, v145, v3, -v151
	v_cvt_pk_bf16_f32 v152, v152, v153
	v_cvt_pk_bf16_f32 v153, v154, v155
	global_store_dwordx2 v[142:143], v[152:153], off
	v_lshl_add_u64 v[142:143], v[142:143], 0, s[40:41]
	v_cndmask_b32_e64 v156, v88, v104, s[10:11]
	v_cndmask_b32_e64 v156, v156, v112, s[8:9]
	v_cndmask_b32_e64 v156, v156, v116, s[0:1]
	v_cndmask_b32_e64 v157, v89, v105, s[10:11]
	v_cndmask_b32_e64 v157, v157, v113, s[8:9]
	v_cndmask_b32_e64 v157, v157, v117, s[0:1]
	v_lshlrev_b32_e32 v148, 16, v156
	v_and_b32_e32 v149, 0xffff0000, v156
	v_lshlrev_b32_e32 v150, 16, v157
	v_and_b32_e32 v151, 0xffff0000, v157
	v_sub_f32_e32 v3, v3, v151
	v_sub_f32_e32 v2, v2, v150
	v_sub_f32_e32 v1, v1, v149
	v_sub_f32_e32 v0, v0, v148
	v_lshlrev_b32_e32 v148, 16, v120
	v_and_b32_e32 v149, 0xffff0000, v120
	v_lshlrev_b32_e32 v150, 16, v121
	v_and_b32_e32 v151, 0xffff0000, v121
	v_add_f32_e32 v2, v2, v150
	v_add_f32_e32 v3, v3, v151
	v_add_f32_e32 v0, v0, v148
	v_add_f32_e32 v1, v1, v149
	v_fma_f32 v152, v145, v0, -v148
	v_fma_f32 v153, v145, v1, -v149
	v_fma_f32 v154, v145, v2, -v150
	v_fma_f32 v155, v145, v3, -v151
	v_cvt_pk_bf16_f32 v152, v152, v153
	v_cvt_pk_bf16_f32 v153, v154, v155
	global_store_dwordx2 v[142:143], v[152:153], off
	v_lshl_add_u64 v[142:143], v[142:143], 0, s[40:41]
	v_cndmask_b32_e64 v156, v90, v106, s[10:11]
	v_cndmask_b32_e64 v156, v156, v114, s[8:9]
	v_cndmask_b32_e64 v156, v156, v118, s[0:1]
	v_cndmask_b32_e64 v157, v91, v107, s[10:11]
	v_cndmask_b32_e64 v157, v157, v115, s[8:9]
	v_cndmask_b32_e64 v157, v157, v119, s[0:1]
	v_lshlrev_b32_e32 v148, 16, v156
	v_and_b32_e32 v149, 0xffff0000, v156
	v_lshlrev_b32_e32 v150, 16, v157
	v_and_b32_e32 v151, 0xffff0000, v157
	v_sub_f32_e32 v3, v3, v151
	v_sub_f32_e32 v2, v2, v150
	v_sub_f32_e32 v1, v1, v149
	v_sub_f32_e32 v0, v0, v148
	v_lshlrev_b32_e32 v148, 16, v122
	v_and_b32_e32 v149, 0xffff0000, v122
	v_lshlrev_b32_e32 v150, 16, v123
	v_and_b32_e32 v151, 0xffff0000, v123
	v_add_f32_e32 v2, v2, v150
	v_add_f32_e32 v3, v3, v151
	v_add_f32_e32 v0, v0, v148
	v_add_f32_e32 v1, v1, v149
	v_fma_f32 v152, v145, v0, -v148
	v_fma_f32 v153, v145, v1, -v149
	v_fma_f32 v154, v145, v2, -v150
	v_fma_f32 v155, v145, v3, -v151
	v_cvt_pk_bf16_f32 v152, v152, v153
	v_cvt_pk_bf16_f32 v153, v154, v155
	global_store_dwordx2 v[142:143], v[152:153], off
	v_lshl_add_u64 v[142:143], v[142:143], 0, s[40:41]
	v_cndmask_b32_e64 v156, v92, v108, s[10:11]
	v_cndmask_b32_e64 v156, v156, v116, s[8:9]
	v_cndmask_b32_e64 v156, v156, v120, s[0:1]
	v_cndmask_b32_e64 v157, v93, v109, s[10:11]
	v_cndmask_b32_e64 v157, v157, v117, s[8:9]
	v_cndmask_b32_e64 v157, v157, v121, s[0:1]
	v_lshlrev_b32_e32 v148, 16, v156
	v_and_b32_e32 v149, 0xffff0000, v156
	v_lshlrev_b32_e32 v150, 16, v157
	v_and_b32_e32 v151, 0xffff0000, v157
	v_sub_f32_e32 v3, v3, v151
	v_sub_f32_e32 v2, v2, v150
	v_sub_f32_e32 v1, v1, v149
	v_sub_f32_e32 v0, v0, v148
	v_lshlrev_b32_e32 v148, 16, v124
	v_and_b32_e32 v149, 0xffff0000, v124
	v_lshlrev_b32_e32 v150, 16, v125
	v_and_b32_e32 v151, 0xffff0000, v125
	v_add_f32_e32 v2, v2, v150
	v_add_f32_e32 v3, v3, v151
	v_add_f32_e32 v0, v0, v148
	v_add_f32_e32 v1, v1, v149
	v_fma_f32 v152, v145, v0, -v148
	v_fma_f32 v153, v145, v1, -v149
	v_fma_f32 v154, v145, v2, -v150
	v_fma_f32 v155, v145, v3, -v151
	v_cvt_pk_bf16_f32 v152, v152, v153
	v_cvt_pk_bf16_f32 v153, v154, v155
	global_store_dwordx2 v[142:143], v[152:153], off
	v_lshl_add_u64 v[142:143], v[142:143], 0, s[40:41]
	v_cndmask_b32_e64 v156, v94, v110, s[10:11]
	v_cndmask_b32_e64 v156, v156, v118, s[8:9]
	v_cndmask_b32_e64 v156, v156, v122, s[0:1]
	v_cndmask_b32_e64 v157, v95, v111, s[10:11]
	v_cndmask_b32_e64 v157, v157, v119, s[8:9]
	v_cndmask_b32_e64 v157, v157, v123, s[0:1]
	v_lshlrev_b32_e32 v148, 16, v156
	v_and_b32_e32 v149, 0xffff0000, v156
	v_lshlrev_b32_e32 v150, 16, v157
	v_and_b32_e32 v151, 0xffff0000, v157
	v_sub_f32_e32 v3, v3, v151
	v_sub_f32_e32 v2, v2, v150
	v_sub_f32_e32 v1, v1, v149
	v_sub_f32_e32 v0, v0, v148
	v_lshlrev_b32_e32 v148, 16, v132
	v_and_b32_e32 v149, 0xffff0000, v132
	v_lshlrev_b32_e32 v150, 16, v133
	v_and_b32_e32 v151, 0xffff0000, v133
	v_add_f32_e32 v2, v2, v150
	v_add_f32_e32 v3, v3, v151
	v_add_f32_e32 v0, v0, v148
	v_add_f32_e32 v1, v1, v149
	v_fma_f32 v152, v145, v0, -v148
	v_fma_f32 v153, v145, v1, -v149
	v_fma_f32 v154, v145, v2, -v150
	v_fma_f32 v155, v145, v3, -v151
	v_cvt_pk_bf16_f32 v152, v152, v153
	v_cvt_pk_bf16_f32 v153, v154, v155
	global_store_dwordx2 v[142:143], v[152:153], off
	v_lshl_add_u64 v[142:143], v[142:143], 0, s[40:41]
	v_cndmask_b32_e64 v156, v96, v112, s[10:11]
	v_cndmask_b32_e64 v156, v156, v120, s[8:9]
	v_cndmask_b32_e64 v156, v156, v124, s[0:1]
	v_cndmask_b32_e64 v157, v97, v113, s[10:11]
	v_cndmask_b32_e64 v157, v157, v121, s[8:9]
	v_cndmask_b32_e64 v157, v157, v125, s[0:1]
	v_lshlrev_b32_e32 v148, 16, v156
	v_and_b32_e32 v149, 0xffff0000, v156
	v_lshlrev_b32_e32 v150, 16, v157
	v_and_b32_e32 v151, 0xffff0000, v157
	v_sub_f32_e32 v3, v3, v151
	v_sub_f32_e32 v2, v2, v150
	v_sub_f32_e32 v1, v1, v149
	v_sub_f32_e32 v0, v0, v148
	v_lshlrev_b32_e32 v148, 16, v134
	v_and_b32_e32 v149, 0xffff0000, v134
	v_lshlrev_b32_e32 v150, 16, v135
	v_and_b32_e32 v151, 0xffff0000, v135
	v_add_f32_e32 v2, v2, v150
	v_add_f32_e32 v3, v3, v151
	v_add_f32_e32 v0, v0, v148
	v_add_f32_e32 v1, v1, v149
	v_fma_f32 v152, v145, v0, -v148
	v_fma_f32 v153, v145, v1, -v149
	v_fma_f32 v154, v145, v2, -v150
	v_fma_f32 v155, v145, v3, -v151
	v_cvt_pk_bf16_f32 v152, v152, v153
	v_cvt_pk_bf16_f32 v153, v154, v155
	global_store_dwordx2 v[142:143], v[152:153], off
	v_lshl_add_u64 v[142:143], v[142:143], 0, s[40:41]
	v_cndmask_b32_e64 v156, v98, v114, s[10:11]
	v_cndmask_b32_e64 v156, v156, v122, s[8:9]
	v_cndmask_b32_e64 v156, v156, v132, s[0:1]
	v_cndmask_b32_e64 v157, v99, v115, s[10:11]
	v_cndmask_b32_e64 v157, v157, v123, s[8:9]
	v_cndmask_b32_e64 v157, v157, v133, s[0:1]
	v_lshlrev_b32_e32 v148, 16, v156
	v_and_b32_e32 v149, 0xffff0000, v156
	v_lshlrev_b32_e32 v150, 16, v157
	v_and_b32_e32 v151, 0xffff0000, v157
	v_sub_f32_e32 v3, v3, v151
	v_sub_f32_e32 v2, v2, v150
	v_sub_f32_e32 v1, v1, v149
	v_sub_f32_e32 v0, v0, v148
	v_lshlrev_b32_e32 v148, 16, v136
	v_and_b32_e32 v149, 0xffff0000, v136
	v_lshlrev_b32_e32 v150, 16, v137
	v_and_b32_e32 v151, 0xffff0000, v137
	v_add_f32_e32 v2, v2, v150
	v_add_f32_e32 v3, v3, v151
	v_add_f32_e32 v0, v0, v148
	v_add_f32_e32 v1, v1, v149
	v_fma_f32 v152, v145, v0, -v148
	v_fma_f32 v153, v145, v1, -v149
	v_fma_f32 v154, v145, v2, -v150
	v_fma_f32 v155, v145, v3, -v151
	v_cvt_pk_bf16_f32 v152, v152, v153
	v_cvt_pk_bf16_f32 v153, v154, v155
	global_store_dwordx2 v[142:143], v[152:153], off
	v_lshl_add_u64 v[142:143], v[142:143], 0, s[40:41]
	v_cndmask_b32_e64 v156, v100, v116, s[10:11]
	v_cndmask_b32_e64 v156, v156, v124, s[8:9]
	v_cndmask_b32_e64 v156, v156, v134, s[0:1]
	v_cndmask_b32_e64 v157, v101, v117, s[10:11]
	v_cndmask_b32_e64 v157, v157, v125, s[8:9]
	v_cndmask_b32_e64 v157, v157, v135, s[0:1]
	v_lshlrev_b32_e32 v148, 16, v156
	v_and_b32_e32 v149, 0xffff0000, v156
	v_lshlrev_b32_e32 v150, 16, v157
	v_and_b32_e32 v151, 0xffff0000, v157
	v_sub_f32_e32 v3, v3, v151
	v_sub_f32_e32 v2, v2, v150
	v_sub_f32_e32 v1, v1, v149
	v_sub_f32_e32 v0, v0, v148
	v_lshlrev_b32_e32 v148, 16, v138
	v_and_b32_e32 v149, 0xffff0000, v138
	v_lshlrev_b32_e32 v150, 16, v139
	v_and_b32_e32 v151, 0xffff0000, v139
	v_add_f32_e32 v2, v2, v150
	v_add_f32_e32 v3, v3, v151
	v_add_f32_e32 v0, v0, v148
	v_add_f32_e32 v1, v1, v149
	v_fma_f32 v152, v145, v0, -v148
	v_fma_f32 v153, v145, v1, -v149
	v_fma_f32 v154, v145, v2, -v150
	v_fma_f32 v155, v145, v3, -v151
	v_cvt_pk_bf16_f32 v152, v152, v153
	v_cvt_pk_bf16_f32 v153, v154, v155
	global_store_dwordx2 v[142:143], v[152:153], off
	s_branch .LBB0_907
